# readout GEMM epilogues: Z/O loads issued ahead with counted vmcnt instead of 16/32 load-wait chains per tile
# speedup vs baseline: 1.0185x; 1.0015x over previous
.LBB0_62:
	v_mbcnt_lo_u32_b32 v0, -1, 0
	v_mbcnt_hi_u32_b32 v0, -1, v0
	v_lshl_add_u32 v0, s69, 6, v0
	s_andn2_b64 vcc, exec, s[40:41]
	v_ashrrev_i32_e32 v130, 2, v0
	v_and_b32_e32 v130, 0xffffffc0, v130
	v_and_or_b32 v131, v0, 15, s45
	v_add_u32_e32 v132, v131, v130
	v_lshrrev_b32_e32 v0, 1, v0
	v_and_b32_e32 v0, 0x78, v0
	v_ashrrev_i32_e32 v133, 31, v132
	v_or_b32_e32 v130, s2, v0
	v_mov_b32_e32 v131, s3
	v_lshlrev_b64 v[134:135], 10, v[132:133]
	v_lshl_add_u64 v[134:135], v[134:135], 0, v[130:131]
	v_lshlrev_b64 v[138:139], 1, v[134:135]
	v_mov_b32_e32 v206, v138
	s_nop 4
	global_load_dwordx4 v[140:143], v206, s[12:13]
	global_load_dwordx4 v[144:147], v206, s[12:13] offset:256
	v_add_u32_e32 v207, 0x8000, v206
	global_load_dwordx4 v[148:151], v207, s[12:13]
	global_load_dwordx4 v[152:155], v207, s[12:13] offset:256
	v_add_u32_e32 v207, 0x10000, v206
	global_load_dwordx4 v[156:159], v207, s[12:13]
	global_load_dwordx4 v[160:163], v207, s[12:13] offset:256
	v_add_u32_e32 v207, 0x18000, v206
	global_load_dwordx4 v[164:167], v207, s[12:13]
	global_load_dwordx4 v[168:171], v207, s[12:13] offset:256
	v_add_u32_e32 v207, 0x40000, v206
	global_load_dwordx4 v[172:175], v207, s[12:13]
	global_load_dwordx4 v[176:179], v207, s[12:13] offset:256
	v_add_u32_e32 v207, 0x48000, v206
	global_load_dwordx4 v[180:183], v207, s[12:13]
	global_load_dwordx4 v[186:189], v207, s[12:13] offset:256
	v_add_u32_e32 v207, 0x50000, v206
	global_load_dwordx4 v[190:193], v207, s[12:13]
	global_load_dwordx4 v[194:197], v207, s[12:13] offset:256
	v_add_u32_e32 v207, 0x58000, v206
	global_load_dwordx4 v[198:201], v207, s[12:13]
	global_load_dwordx4 v[202:205], v207, s[12:13] offset:256
	v_readlane_b32 s2, v255, 18
	v_readlane_b32 s3, v255, 19
	s_mov_b32 s45, s8
	s_waitcnt vmcnt(15)
	v_lshlrev_b32_e32 v0, 16, v140
	v_mul_f32_e32 v0, v126, v0
	v_and_b32_e32 v126, 0xffff0000, v140
	v_mul_f32_e32 v126, v127, v126
	v_lshlrev_b32_e32 v127, 16, v141
	v_mul_f32_e32 v127, v128, v127
	v_and_b32_e32 v128, 0xffff0000, v141
	v_mul_f32_e32 v128, v129, v128
	v_lshlrev_b32_e32 v129, 16, v142
	v_mul_f32_e32 v129, v122, v129
	v_and_b32_e32 v122, 0xffff0000, v142
	v_mul_f32_e32 v133, v123, v122
	v_lshlrev_b32_e32 v122, 16, v143
	v_mul_f32_e32 v134, v124, v122
	v_and_b32_e32 v122, 0xffff0000, v143
	v_mul_f32_e32 v125, v125, v122
	v_cvt_pk_bf16_f32 v122, v0, v126
	v_cvt_pk_bf16_f32 v123, v127, v128
	v_lshl_add_u64 v[126:127], s[2:3], 0, v[138:139]
	v_or_b32_e32 v138, 0x100, v138
	v_cvt_pk_bf16_f32 v124, v129, v133
	v_cvt_pk_bf16_f32 v125, v134, v125
	global_store_dwordx4 v[126:127], v[122:125], off
	s_nop 1
	s_waitcnt vmcnt(15)
	v_lshlrev_b32_e32 v0, 16, v144
	v_mul_f32_e32 v0, v118, v0
	v_and_b32_e32 v118, 0xffff0000, v144
	v_mul_f32_e32 v118, v119, v118
	v_lshlrev_b32_e32 v119, 16, v145
	v_mul_f32_e32 v119, v120, v119
	v_and_b32_e32 v120, 0xffff0000, v145
	v_mul_f32_e32 v120, v121, v120
	v_lshlrev_b32_e32 v121, 16, v146
	v_mul_f32_e32 v121, v114, v121
	v_and_b32_e32 v114, 0xffff0000, v146
	v_mul_f32_e32 v122, v115, v114
	v_lshlrev_b32_e32 v114, 16, v147
	v_mul_f32_e32 v123, v116, v114
	v_and_b32_e32 v114, 0xffff0000, v147
	v_mul_f32_e32 v117, v117, v114
	v_cvt_pk_bf16_f32 v114, v0, v118
	v_cvt_pk_bf16_f32 v115, v119, v120
	v_lshl_add_u64 v[118:119], s[2:3], 0, v[138:139]
	v_cvt_pk_bf16_f32 v116, v121, v122
	v_cvt_pk_bf16_f32 v117, v123, v117
	global_store_dwordx4 v[118:119], v[114:117], off
	s_nop 1
	v_or_b32_e32 v114, 16, v132
	v_ashrrev_i32_e32 v115, 31, v114
	v_lshlrev_b64 v[114:115], 10, v[114:115]
	v_lshl_add_u64 v[114:115], v[114:115], 0, v[130:131]
	v_lshlrev_b64 v[114:115], 1, v[114:115]
	s_waitcnt vmcnt(15)
	v_lshlrev_b32_e32 v0, 16, v148
	v_mul_f32_e32 v0, v110, v0
	v_and_b32_e32 v110, 0xffff0000, v148
	v_mul_f32_e32 v110, v111, v110
	v_lshlrev_b32_e32 v111, 16, v149
	v_mul_f32_e32 v111, v112, v111
	v_and_b32_e32 v112, 0xffff0000, v149
	v_mul_f32_e32 v112, v113, v112
	v_lshlrev_b32_e32 v113, 16, v150
	v_mul_f32_e32 v113, v106, v113
	v_and_b32_e32 v106, 0xffff0000, v150
	v_mul_f32_e32 v116, v107, v106
	v_lshlrev_b32_e32 v106, 16, v151
	v_mul_f32_e32 v117, v108, v106
	v_and_b32_e32 v106, 0xffff0000, v151
	v_mul_f32_e32 v109, v109, v106
	v_cvt_pk_bf16_f32 v106, v0, v110
	v_cvt_pk_bf16_f32 v107, v111, v112
	v_lshl_add_u64 v[110:111], s[2:3], 0, v[114:115]
	v_or_b32_e32 v114, 0x100, v114
	v_cvt_pk_bf16_f32 v108, v113, v116
	v_cvt_pk_bf16_f32 v109, v117, v109
	global_store_dwordx4 v[110:111], v[106:109], off
	s_nop 1
	s_waitcnt vmcnt(15)
	v_lshlrev_b32_e32 v0, 16, v152
	v_mul_f32_e32 v0, v102, v0
	v_and_b32_e32 v102, 0xffff0000, v152
	v_mul_f32_e32 v102, v103, v102
	v_lshlrev_b32_e32 v103, 16, v153
	v_mul_f32_e32 v103, v104, v103
	v_and_b32_e32 v104, 0xffff0000, v153
	v_mul_f32_e32 v104, v105, v104
	v_lshlrev_b32_e32 v105, 16, v154
	v_mul_f32_e32 v105, v98, v105
	v_and_b32_e32 v98, 0xffff0000, v154
	v_mul_f32_e32 v106, v99, v98
	v_lshlrev_b32_e32 v98, 16, v155
	v_mul_f32_e32 v107, v100, v98
	v_and_b32_e32 v98, 0xffff0000, v155
	v_mul_f32_e32 v101, v101, v98
	v_cvt_pk_bf16_f32 v98, v0, v102
	v_cvt_pk_bf16_f32 v99, v103, v104
	v_lshl_add_u64 v[102:103], s[2:3], 0, v[114:115]
	v_cvt_pk_bf16_f32 v100, v105, v106
	v_cvt_pk_bf16_f32 v101, v107, v101
	global_store_dwordx4 v[102:103], v[98:101], off
	s_nop 1
	v_or_b32_e32 v98, 32, v132
	v_ashrrev_i32_e32 v99, 31, v98
	v_lshlrev_b64 v[98:99], 10, v[98:99]
	v_lshl_add_u64 v[98:99], v[98:99], 0, v[130:131]
	v_lshlrev_b64 v[98:99], 1, v[98:99]
	s_waitcnt vmcnt(15)
	v_lshlrev_b32_e32 v0, 16, v156
	v_mul_f32_e32 v0, v94, v0
	v_and_b32_e32 v94, 0xffff0000, v156
	v_mul_f32_e32 v94, v95, v94
	v_lshlrev_b32_e32 v95, 16, v157
	v_mul_f32_e32 v95, v96, v95
	v_and_b32_e32 v96, 0xffff0000, v157
	v_mul_f32_e32 v96, v97, v96
	v_lshlrev_b32_e32 v97, 16, v158
	v_mul_f32_e32 v97, v90, v97
	v_and_b32_e32 v90, 0xffff0000, v158
	v_mul_f32_e32 v100, v91, v90
	v_lshlrev_b32_e32 v90, 16, v159
	v_mul_f32_e32 v101, v92, v90
	v_and_b32_e32 v90, 0xffff0000, v159
	v_mul_f32_e32 v93, v93, v90
	v_cvt_pk_bf16_f32 v90, v0, v94
	v_cvt_pk_bf16_f32 v91, v95, v96
	v_lshl_add_u64 v[94:95], s[2:3], 0, v[98:99]
	v_or_b32_e32 v98, 0x100, v98
	v_cvt_pk_bf16_f32 v92, v97, v100
	v_cvt_pk_bf16_f32 v93, v101, v93
	global_store_dwordx4 v[94:95], v[90:93], off
	s_nop 1
	s_waitcnt vmcnt(15)
	v_lshlrev_b32_e32 v0, 16, v160
	v_mul_f32_e32 v0, v86, v0
	v_and_b32_e32 v86, 0xffff0000, v160
	v_mul_f32_e32 v86, v87, v86
	v_lshlrev_b32_e32 v87, 16, v161
	v_mul_f32_e32 v87, v88, v87
	v_and_b32_e32 v88, 0xffff0000, v161
	v_mul_f32_e32 v88, v89, v88
	v_lshlrev_b32_e32 v89, 16, v162
	v_mul_f32_e32 v89, v82, v89
	v_and_b32_e32 v82, 0xffff0000, v162
	v_mul_f32_e32 v90, v83, v82
	v_lshlrev_b32_e32 v82, 16, v163
	v_mul_f32_e32 v91, v84, v82
	v_and_b32_e32 v82, 0xffff0000, v163
	v_mul_f32_e32 v85, v85, v82
	v_cvt_pk_bf16_f32 v82, v0, v86
	v_cvt_pk_bf16_f32 v83, v87, v88
	v_lshl_add_u64 v[86:87], s[2:3], 0, v[98:99]
	v_cvt_pk_bf16_f32 v84, v89, v90
	v_cvt_pk_bf16_f32 v85, v91, v85
	global_store_dwordx4 v[86:87], v[82:85], off
	s_nop 1
	v_or_b32_e32 v82, 48, v132
	v_ashrrev_i32_e32 v83, 31, v82
	v_lshlrev_b64 v[82:83], 10, v[82:83]
	v_lshl_add_u64 v[82:83], v[82:83], 0, v[130:131]
	v_lshlrev_b64 v[82:83], 1, v[82:83]
	s_waitcnt vmcnt(15)
	v_lshlrev_b32_e32 v0, 16, v164
	v_mul_f32_e32 v0, v78, v0
	v_and_b32_e32 v78, 0xffff0000, v164
	v_mul_f32_e32 v78, v79, v78
	v_lshlrev_b32_e32 v79, 16, v165
	v_mul_f32_e32 v79, v80, v79
	v_and_b32_e32 v80, 0xffff0000, v165
	v_mul_f32_e32 v80, v81, v80
	v_lshlrev_b32_e32 v81, 16, v166
	v_mul_f32_e32 v81, v74, v81
	v_and_b32_e32 v74, 0xffff0000, v166
	v_mul_f32_e32 v84, v75, v74
	v_lshlrev_b32_e32 v74, 16, v167
	v_mul_f32_e32 v85, v76, v74
	v_and_b32_e32 v74, 0xffff0000, v167
	v_mul_f32_e32 v77, v77, v74
	v_cvt_pk_bf16_f32 v74, v0, v78
	v_cvt_pk_bf16_f32 v75, v79, v80
	v_lshl_add_u64 v[78:79], s[2:3], 0, v[82:83]
	v_or_b32_e32 v82, 0x100, v82
	v_cvt_pk_bf16_f32 v76, v81, v84
	v_cvt_pk_bf16_f32 v77, v85, v77
	global_store_dwordx4 v[78:79], v[74:77], off
	s_nop 1
	s_waitcnt vmcnt(15)
	v_lshlrev_b32_e32 v0, 16, v168
	v_mul_f32_e32 v0, v70, v0
	v_and_b32_e32 v70, 0xffff0000, v168
	v_mul_f32_e32 v70, v71, v70
	v_lshlrev_b32_e32 v71, 16, v169
	v_mul_f32_e32 v71, v72, v71
	v_and_b32_e32 v72, 0xffff0000, v169
	v_mul_f32_e32 v72, v73, v72
	v_lshlrev_b32_e32 v73, 16, v170
	v_mul_f32_e32 v73, v66, v73
	v_and_b32_e32 v66, 0xffff0000, v170
	v_mul_f32_e32 v74, v67, v66
	v_lshlrev_b32_e32 v66, 16, v171
	v_mul_f32_e32 v75, v68, v66
	v_and_b32_e32 v66, 0xffff0000, v171
	v_mul_f32_e32 v69, v69, v66
	v_cvt_pk_bf16_f32 v66, v0, v70
	v_cvt_pk_bf16_f32 v67, v71, v72
	v_lshl_add_u64 v[70:71], s[2:3], 0, v[82:83]
	v_cvt_pk_bf16_f32 v68, v73, v74
	v_cvt_pk_bf16_f32 v69, v75, v69
	global_store_dwordx4 v[70:71], v[66:69], off
	s_nop 1
	v_add_u32_e32 v66, 0x80, v132
	v_ashrrev_i32_e32 v67, 31, v66
	v_lshlrev_b64 v[66:67], 10, v[66:67]
	v_lshl_add_u64 v[66:67], v[66:67], 0, v[130:131]
	v_lshlrev_b64 v[66:67], 1, v[66:67]
	s_waitcnt vmcnt(15)
	v_lshlrev_b32_e32 v0, 16, v172
	v_mul_f32_e32 v0, v62, v0
	v_and_b32_e32 v62, 0xffff0000, v172
	v_mul_f32_e32 v62, v63, v62
	v_lshlrev_b32_e32 v63, 16, v173
	v_mul_f32_e32 v63, v64, v63
	v_and_b32_e32 v64, 0xffff0000, v173
	v_mul_f32_e32 v64, v65, v64
	v_lshlrev_b32_e32 v65, 16, v174
	v_mul_f32_e32 v65, v58, v65
	v_and_b32_e32 v58, 0xffff0000, v174
	v_mul_f32_e32 v68, v59, v58
	v_lshlrev_b32_e32 v58, 16, v175
	v_mul_f32_e32 v69, v60, v58
	v_and_b32_e32 v58, 0xffff0000, v175
	v_mul_f32_e32 v61, v61, v58
	v_cvt_pk_bf16_f32 v58, v0, v62
	v_cvt_pk_bf16_f32 v59, v63, v64
	v_lshl_add_u64 v[62:63], s[2:3], 0, v[66:67]
	v_or_b32_e32 v66, 0x100, v66
	v_cvt_pk_bf16_f32 v60, v65, v68
	v_cvt_pk_bf16_f32 v61, v69, v61
	global_store_dwordx4 v[62:63], v[58:61], off
	s_nop 1
	s_waitcnt vmcnt(15)
	v_lshlrev_b32_e32 v0, 16, v176
	v_mul_f32_e32 v0, v54, v0
	v_and_b32_e32 v54, 0xffff0000, v176
	v_mul_f32_e32 v54, v55, v54
	v_lshlrev_b32_e32 v55, 16, v177
	v_mul_f32_e32 v55, v56, v55
	v_and_b32_e32 v56, 0xffff0000, v177
	v_mul_f32_e32 v56, v57, v56
	v_lshlrev_b32_e32 v57, 16, v178
	v_mul_f32_e32 v57, v50, v57
	v_and_b32_e32 v50, 0xffff0000, v178
	v_mul_f32_e32 v58, v51, v50
	v_lshlrev_b32_e32 v50, 16, v179
	v_mul_f32_e32 v59, v52, v50
	v_and_b32_e32 v50, 0xffff0000, v179
	v_mul_f32_e32 v53, v53, v50
	v_cvt_pk_bf16_f32 v50, v0, v54
	v_cvt_pk_bf16_f32 v51, v55, v56
	v_lshl_add_u64 v[54:55], s[2:3], 0, v[66:67]
	v_cvt_pk_bf16_f32 v52, v57, v58
	v_cvt_pk_bf16_f32 v53, v59, v53
	global_store_dwordx4 v[54:55], v[50:53], off
	s_nop 1
	v_add_u32_e32 v50, 0x90, v132
	v_ashrrev_i32_e32 v51, 31, v50
	v_lshlrev_b64 v[50:51], 10, v[50:51]
	v_lshl_add_u64 v[50:51], v[50:51], 0, v[130:131]
	v_lshlrev_b64 v[50:51], 1, v[50:51]
	s_waitcnt vmcnt(15)
	v_lshlrev_b32_e32 v0, 16, v180
	v_mul_f32_e32 v0, v46, v0
	v_and_b32_e32 v46, 0xffff0000, v180
	v_mul_f32_e32 v46, v47, v46
	v_lshlrev_b32_e32 v47, 16, v181
	v_mul_f32_e32 v47, v48, v47
	v_and_b32_e32 v48, 0xffff0000, v181
	v_mul_f32_e32 v48, v49, v48
	v_lshlrev_b32_e32 v49, 16, v182
	v_mul_f32_e32 v49, v42, v49
	v_and_b32_e32 v42, 0xffff0000, v182
	v_mul_f32_e32 v52, v43, v42
	v_lshlrev_b32_e32 v42, 16, v183
	v_mul_f32_e32 v53, v44, v42
	v_and_b32_e32 v42, 0xffff0000, v183
	v_mul_f32_e32 v45, v45, v42
	v_cvt_pk_bf16_f32 v42, v0, v46
	v_cvt_pk_bf16_f32 v43, v47, v48
	v_lshl_add_u64 v[46:47], s[2:3], 0, v[50:51]
	v_or_b32_e32 v50, 0x100, v50
	v_cvt_pk_bf16_f32 v44, v49, v52
	v_cvt_pk_bf16_f32 v45, v53, v45
	global_store_dwordx4 v[46:47], v[42:45], off
	s_nop 1
	s_waitcnt vmcnt(15)
	v_lshlrev_b32_e32 v0, 16, v186
	v_mul_f32_e32 v0, v38, v0
	v_and_b32_e32 v38, 0xffff0000, v186
	v_mul_f32_e32 v38, v39, v38
	v_lshlrev_b32_e32 v39, 16, v187
	v_mul_f32_e32 v39, v40, v39
	v_and_b32_e32 v40, 0xffff0000, v187
	v_mul_f32_e32 v40, v41, v40
	v_lshlrev_b32_e32 v41, 16, v188
	v_mul_f32_e32 v41, v34, v41
	v_and_b32_e32 v34, 0xffff0000, v188
	v_mul_f32_e32 v42, v35, v34
	v_lshlrev_b32_e32 v34, 16, v189
	v_mul_f32_e32 v43, v36, v34
	v_and_b32_e32 v34, 0xffff0000, v189
	v_mul_f32_e32 v37, v37, v34
	v_cvt_pk_bf16_f32 v34, v0, v38
	v_cvt_pk_bf16_f32 v35, v39, v40
	v_lshl_add_u64 v[38:39], s[2:3], 0, v[50:51]
	v_cvt_pk_bf16_f32 v36, v41, v42
	v_cvt_pk_bf16_f32 v37, v43, v37
	global_store_dwordx4 v[38:39], v[34:37], off
	s_nop 1
	v_add_u32_e32 v34, 0xa0, v132
	v_ashrrev_i32_e32 v35, 31, v34
	v_lshlrev_b64 v[34:35], 10, v[34:35]
	v_lshl_add_u64 v[34:35], v[34:35], 0, v[130:131]
	v_lshlrev_b64 v[34:35], 1, v[34:35]
	s_waitcnt vmcnt(15)
	v_lshlrev_b32_e32 v0, 16, v190
	v_mul_f32_e32 v0, v30, v0
	v_and_b32_e32 v30, 0xffff0000, v190
	v_mul_f32_e32 v30, v31, v30
	v_lshlrev_b32_e32 v31, 16, v191
	v_mul_f32_e32 v31, v32, v31
	v_and_b32_e32 v32, 0xffff0000, v191
	v_mul_f32_e32 v32, v33, v32
	v_lshlrev_b32_e32 v33, 16, v192
	v_mul_f32_e32 v33, v26, v33
	v_and_b32_e32 v26, 0xffff0000, v192
	v_mul_f32_e32 v36, v27, v26
	v_lshlrev_b32_e32 v26, 16, v193
	v_mul_f32_e32 v37, v28, v26
	v_and_b32_e32 v26, 0xffff0000, v193
	v_mul_f32_e32 v29, v29, v26
	v_cvt_pk_bf16_f32 v26, v0, v30
	v_cvt_pk_bf16_f32 v27, v31, v32
	v_lshl_add_u64 v[30:31], s[2:3], 0, v[34:35]
	v_or_b32_e32 v34, 0x100, v34
	v_cvt_pk_bf16_f32 v28, v33, v36
	v_cvt_pk_bf16_f32 v29, v37, v29
	global_store_dwordx4 v[30:31], v[26:29], off
	s_nop 1
	s_waitcnt vmcnt(15)
	v_lshlrev_b32_e32 v0, 16, v194
	v_mul_f32_e32 v0, v22, v0
	v_and_b32_e32 v22, 0xffff0000, v194
	v_mul_f32_e32 v22, v23, v22
	v_lshlrev_b32_e32 v23, 16, v195
	v_mul_f32_e32 v23, v24, v23
	v_and_b32_e32 v24, 0xffff0000, v195
	v_mul_f32_e32 v24, v25, v24
	v_lshlrev_b32_e32 v25, 16, v196
	v_mul_f32_e32 v25, v18, v25
	v_and_b32_e32 v18, 0xffff0000, v196
	v_mul_f32_e32 v26, v19, v18
	v_lshlrev_b32_e32 v18, 16, v197
	v_mul_f32_e32 v27, v20, v18
	v_and_b32_e32 v18, 0xffff0000, v197
	v_mul_f32_e32 v21, v21, v18
	v_cvt_pk_bf16_f32 v18, v0, v22
	v_cvt_pk_bf16_f32 v19, v23, v24
	v_lshl_add_u64 v[22:23], s[2:3], 0, v[34:35]
	v_cvt_pk_bf16_f32 v20, v25, v26
	v_cvt_pk_bf16_f32 v21, v27, v21
	global_store_dwordx4 v[22:23], v[18:21], off
	s_nop 1
	v_add_u32_e32 v18, 0xb0, v132
	v_ashrrev_i32_e32 v19, 31, v18
	v_lshlrev_b64 v[18:19], 10, v[18:19]
	v_lshl_add_u64 v[18:19], v[18:19], 0, v[130:131]
	v_lshlrev_b64 v[18:19], 1, v[18:19]
	s_waitcnt vmcnt(15)
	v_lshlrev_b32_e32 v0, 16, v198
	v_mul_f32_e32 v0, v14, v0
	v_and_b32_e32 v14, 0xffff0000, v198
	v_mul_f32_e32 v14, v15, v14
	v_lshlrev_b32_e32 v15, 16, v199
	v_mul_f32_e32 v15, v16, v15
	v_and_b32_e32 v16, 0xffff0000, v199
	v_mul_f32_e32 v16, v17, v16
	v_lshlrev_b32_e32 v17, 16, v200
	v_mul_f32_e32 v17, v10, v17
	v_and_b32_e32 v10, 0xffff0000, v200
	v_mul_f32_e32 v20, v11, v10
	v_lshlrev_b32_e32 v10, 16, v201
	v_mul_f32_e32 v21, v12, v10
	v_and_b32_e32 v10, 0xffff0000, v201
	v_mul_f32_e32 v13, v13, v10
	v_cvt_pk_bf16_f32 v10, v0, v14
	v_cvt_pk_bf16_f32 v11, v15, v16
	v_lshl_add_u64 v[14:15], s[2:3], 0, v[18:19]
	v_or_b32_e32 v18, 0x100, v18
	v_cvt_pk_bf16_f32 v12, v17, v20
	v_cvt_pk_bf16_f32 v13, v21, v13
	global_store_dwordx4 v[14:15], v[10:13], off
	s_nop 1
	s_waitcnt vmcnt(15)
	v_lshlrev_b32_e32 v0, 16, v202
	v_mul_f32_e32 v0, v6, v0
	v_and_b32_e32 v6, 0xffff0000, v202
	v_mul_f32_e32 v6, v7, v6
	v_lshlrev_b32_e32 v7, 16, v203
	v_mul_f32_e32 v7, v8, v7
	v_and_b32_e32 v8, 0xffff0000, v203
	v_mul_f32_e32 v8, v9, v8
	v_lshlrev_b32_e32 v9, 16, v204
	v_mul_f32_e32 v9, v2, v9
	v_and_b32_e32 v2, 0xffff0000, v204
	v_mul_f32_e32 v10, v3, v2
	v_lshlrev_b32_e32 v2, 16, v205
	v_mul_f32_e32 v11, v4, v2
	v_and_b32_e32 v2, 0xffff0000, v205
	v_mul_f32_e32 v5, v5, v2
	v_cvt_pk_bf16_f32 v2, v0, v6
	v_cvt_pk_bf16_f32 v3, v7, v8
	v_lshl_add_u64 v[6:7], s[2:3], 0, v[18:19]
	v_cvt_pk_bf16_f32 v4, v9, v10
	v_cvt_pk_bf16_f32 v5, v11, v5
	global_store_dwordx4 v[6:7], v[2:5], off
	v_mbcnt_lo_u32_b32 v130, -1, 0
	v_mbcnt_hi_u32_b32 v130, -1, v130
	v_lshl_add_u32 v130, s69, 6, v130
	s_mov_b32 s2, s38
	v_lshlrev_b32_e32 v12, 4, v130
	v_bfe_i32 v2, v130, 27, 1
	v_lshrrev_b32_e32 v2, 22, v2
	v_add_u32_e32 v2, v12, v2
	v_and_b32_e32 v2, 0xfffffc00, v2
	v_ashrrev_i32_e32 v0, 31, v130
	v_sub_u32_e32 v2, v12, v2
	v_lshrrev_b32_e32 v0, 26, v0
	v_lshrrev_b32_e32 v3, 4, v2
	v_add_u32_e32 v0, v130, v0
	v_bitop3_b32 v3, v3, v2, 32 bitop3:0x6c
	v_ashrrev_i32_e32 v2, 31, v2
	v_ashrrev_i32_e32 v0, 6, v0
	v_lshrrev_b32_e32 v2, 26, v2
	v_lshlrev_b32_e32 v4, 3, v0
	v_add_u32_e32 v2, v3, v2
	v_and_b32_e32 v4, -16, v4
	v_ashrrev_i32_e32 v2, 6, v2
	v_add_u32_e32 v4, v2, v4
	v_mul_i32_i24_e32 v2, 64, v2
	v_lshlrev_b32_e32 v0, 5, v0
	v_sub_u32_e32 v2, v3, v2
	v_add_u32_e32 v13, 0x2000, v12
	v_and_b32_e32 v0, 32, v0
	v_ashrrev_i16_sdwa v2, v217, sext(v2) dst_sel:DWORD dst_unused:UNUSED_PAD src0_sel:DWORD src1_sel:BYTE_0
	v_add_u32_sdwa v0, v0, sext(v2) dst_sel:DWORD dst_unused:UNUSED_PAD src0_sel:DWORD src1_sel:WORD_0
	v_ashrrev_i32_e32 v2, 31, v13
	v_lshrrev_b32_e32 v2, 22, v2
	v_add_u32_e32 v2, v13, v2
	v_ashrrev_i32_e32 v2, 10, v2
	v_mul_i32_i24_e32 v3, 0x400, v2
	v_sub_u32_e32 v3, v13, v3
	v_lshrrev_b32_e32 v5, 4, v3
	v_bitop3_b32 v3, v5, v3, 32 bitop3:0x6c
	v_ashrrev_i32_e32 v6, 31, v3
	v_lshrrev_b32_e32 v6, 26, v6
	v_add_u32_e32 v6, v3, v6
	v_ashrrev_i32_e32 v7, 6, v6
	v_and_b32_e32 v6, 0xc0, v6
	v_lshlrev_b32_e32 v5, 3, v2
	v_lshlrev_b32_e32 v2, 5, v2
	v_sub_u32_e32 v3, v3, v6
	v_and_b32_e32 v5, -16, v5
	v_and_b32_e32 v2, 32, v2
	v_ashrrev_i16_sdwa v3, v217, sext(v3) dst_sel:DWORD dst_unused:UNUSED_PAD src0_sel:DWORD src1_sel:BYTE_0
	v_add_u32_e32 v5, v7, v5
	v_add_u32_sdwa v2, v2, sext(v3) dst_sel:DWORD dst_unused:UNUSED_PAD src0_sel:DWORD src1_sel:WORD_0
	v_mul_lo_u32 v3, v4, s59
	v_add_lshl_u32 v11, v0, v3, 1
	v_mul_lo_u32 v3, v5, s59
	v_add_lshl_u32 v10, v2, v3, 1
	v_lshlrev_b32_e32 v3, 9, v4
	v_lshl_add_u32 v0, v0, 1, v3
	v_lshlrev_b32_e32 v3, 9, v5
	v_ashrrev_i32_e32 v14, 6, v130
	v_lshl_add_u32 v2, v2, 1, v3
	s_cbranch_vccz .LBB0_71

.LBB0_73:
	v_mbcnt_lo_u32_b32 v0, -1, 0
	v_mbcnt_hi_u32_b32 v0, -1, v0
	v_lshl_add_u32 v0, s69, 6, v0
	v_readlane_b32 s20, v255, 16
	v_ashrrev_i32_e32 v130, 2, v0
	v_and_b32_e32 v130, 0xffffffc0, v130
	v_and_or_b32 v131, v0, 15, s43
	v_add_u32_e32 v132, v131, v130
	v_lshrrev_b32_e32 v0, 1, v0
	v_and_b32_e32 v0, 0x78, v0
	v_ashrrev_i32_e32 v133, 31, v132
	v_or_b32_e32 v130, s2, v0
	v_mov_b32_e32 v131, s3
	v_lshlrev_b64 v[134:135], 10, v[132:133]
	v_lshl_add_u64 v[134:135], v[134:135], 0, v[130:131]
	v_lshlrev_b64 v[138:139], 1, v[134:135]
	v_readlane_b32 s21, v255, 17
	v_readlane_b32 s2, v255, 18
	v_readlane_b32 s3, v255, 19
	v_mov_b32_e32 v206, v138
	s_nop 4
	global_load_dwordx4 v[152:155], v206, s[20:21]
	global_load_dwordx4 v[156:159], v206, s[2:3]
	global_load_dwordx4 v[160:163], v206, s[20:21] offset:256
	global_load_dwordx4 v[164:167], v206, s[2:3] offset:256
	v_add_u32_e32 v207, 0x8000, v206
	global_load_dwordx4 v[168:171], v207, s[20:21]
	global_load_dwordx4 v[172:175], v207, s[2:3]
	global_load_dwordx4 v[176:179], v207, s[20:21] offset:256
	global_load_dwordx4 v[180:183], v207, s[2:3] offset:256
	v_add_u32_e32 v207, 0x10000, v206
	global_load_dwordx4 v[186:189], v207, s[20:21]
	global_load_dwordx4 v[190:193], v207, s[2:3]
	global_load_dwordx4 v[194:197], v207, s[20:21] offset:256
	global_load_dwordx4 v[198:201], v207, s[2:3] offset:256
	v_add_u32_e32 v207, 0x18000, v206
	global_load_dwordx4 v[202:205], v207, s[20:21]
	global_load_dwordx4 v[218:221], v207, s[2:3]
	global_load_dwordx4 v[222:225], v207, s[20:21] offset:256
	global_load_dwordx4 v[226:229], v207, s[2:3] offset:256
	v_add_u32_e32 v207, 0x40000, v206
	global_load_dwordx4 v[230:233], v207, s[20:21]
	global_load_dwordx4 v[234:237], v207, s[2:3]
	global_load_dwordx4 v[238:241], v207, s[20:21] offset:256
	global_load_dwordx4 v[242:245], v207, s[2:3] offset:256
	v_lshl_add_u64 v[148:149], s[2:3], 0, v[138:139]
	v_or_b32_e32 v138, 0x100, v138
	s_and_b64 vcc, exec, s[22:23]
	s_mov_b32 s43, s8
	s_waitcnt vmcnt(19)
	v_lshlrev_b32_e32 v140, 16, v152
	v_and_b32_e32 v141, 0xffff0000, v152
	v_lshlrev_b32_e32 v142, 16, v153
	v_and_b32_e32 v143, 0xffff0000, v153
	v_lshlrev_b32_e32 v144, 16, v154
	v_and_b32_e32 v145, 0xffff0000, v154
	v_lshlrev_b32_e32 v146, 16, v155
	v_and_b32_e32 v147, 0xffff0000, v155
	s_waitcnt vmcnt(18)
	v_lshlrev_b32_e32 v150, 16, v156
	v_and_b32_e32 v151, 0xffff0000, v156
	v_lshlrev_b32_e32 v134, 16, v157
	v_and_b32_e32 v135, 0xffff0000, v157
	v_pk_fma_f32 v[128:129], v[128:129], v[142:143], v[134:135]
	v_lshlrev_b32_e32 v134, 16, v158
	v_and_b32_e32 v135, 0xffff0000, v158
	v_lshlrev_b32_e32 v136, 16, v159
	v_and_b32_e32 v137, 0xffff0000, v159
	v_pk_fma_f32 v[126:127], v[126:127], v[140:141], v[150:151]
	v_pk_fma_f32 v[136:137], v[124:125], v[146:147], v[136:137]
	v_pk_fma_f32 v[124:125], v[122:123], v[144:145], v[134:135]
	v_cvt_pk_bf16_f32 v122, v126, v127
	v_cvt_pk_bf16_f32 v123, v128, v129
	s_nop 0
	v_cvt_pk_bf16_f32 v124, v124, v125
	v_cvt_pk_bf16_f32 v125, v136, v137
	global_store_dwordx4 v[148:149], v[122:125], off
	s_nop 1
	v_add_u32_e32 v207, 0x48000, v206
	global_load_dwordx4 v[152:155], v207, s[20:21]
	global_load_dwordx4 v[156:159], v207, s[2:3]
	v_lshl_add_u64 v[138:139], s[2:3], 0, v[138:139]
	s_waitcnt vmcnt(20)
	v_lshlrev_b32_e32 v126, 16, v160
	v_and_b32_e32 v127, 0xffff0000, v160
	v_lshlrev_b32_e32 v128, 16, v161
	v_and_b32_e32 v129, 0xffff0000, v161
	v_lshlrev_b32_e32 v134, 16, v162
	v_and_b32_e32 v135, 0xffff0000, v162
	v_lshlrev_b32_e32 v136, 16, v163
	v_and_b32_e32 v137, 0xffff0000, v163
	s_waitcnt vmcnt(19)
	v_lshlrev_b32_e32 v140, 16, v164
	v_and_b32_e32 v141, 0xffff0000, v164
	v_lshlrev_b32_e32 v122, 16, v165
	v_and_b32_e32 v123, 0xffff0000, v165
	v_pk_fma_f32 v[120:121], v[120:121], v[128:129], v[122:123]
	v_lshlrev_b32_e32 v122, 16, v166
	v_and_b32_e32 v123, 0xffff0000, v166
	v_lshlrev_b32_e32 v124, 16, v167
	v_and_b32_e32 v125, 0xffff0000, v167
	v_pk_fma_f32 v[118:119], v[118:119], v[126:127], v[140:141]
	v_pk_fma_f32 v[124:125], v[116:117], v[136:137], v[124:125]
	v_pk_fma_f32 v[116:117], v[114:115], v[134:135], v[122:123]
	v_cvt_pk_bf16_f32 v114, v118, v119
	v_cvt_pk_bf16_f32 v115, v120, v121
	s_nop 0
	v_cvt_pk_bf16_f32 v116, v116, v117
	v_cvt_pk_bf16_f32 v117, v124, v125
	global_store_dwordx4 v[138:139], v[114:117], off
	s_nop 1
	global_load_dwordx4 v[160:163], v207, s[20:21] offset:256
	global_load_dwordx4 v[164:167], v207, s[2:3] offset:256
	v_or_b32_e32 v114, 16, v132
	v_ashrrev_i32_e32 v115, 31, v114
	v_lshlrev_b64 v[114:115], 10, v[114:115]
	v_lshl_add_u64 v[114:115], v[114:115], 0, v[130:131]
	v_lshlrev_b64 v[114:115], 1, v[114:115]
	v_lshl_add_u64 v[128:129], s[2:3], 0, v[114:115]
	v_or_b32_e32 v114, 0x100, v114
	s_waitcnt vmcnt(21)
	v_lshlrev_b32_e32 v120, 16, v168
	v_and_b32_e32 v121, 0xffff0000, v168
	v_lshlrev_b32_e32 v122, 16, v169
	v_and_b32_e32 v123, 0xffff0000, v169
	v_lshlrev_b32_e32 v124, 16, v170
	v_and_b32_e32 v125, 0xffff0000, v170
	v_lshlrev_b32_e32 v126, 16, v171
	v_and_b32_e32 v127, 0xffff0000, v171
	s_waitcnt vmcnt(20)
	v_lshlrev_b32_e32 v134, 16, v172
	v_and_b32_e32 v135, 0xffff0000, v172
	v_lshlrev_b32_e32 v116, 16, v173
	v_and_b32_e32 v117, 0xffff0000, v173
	v_pk_fma_f32 v[112:113], v[112:113], v[122:123], v[116:117]
	v_lshlrev_b32_e32 v116, 16, v174
	v_and_b32_e32 v117, 0xffff0000, v174
	v_lshlrev_b32_e32 v118, 16, v175
	v_and_b32_e32 v119, 0xffff0000, v175
	v_pk_fma_f32 v[110:111], v[110:111], v[120:121], v[134:135]
	v_pk_fma_f32 v[118:119], v[108:109], v[126:127], v[118:119]
	v_pk_fma_f32 v[108:109], v[106:107], v[124:125], v[116:117]
	v_cvt_pk_bf16_f32 v106, v110, v111
	v_cvt_pk_bf16_f32 v107, v112, v113
	s_nop 0
	v_cvt_pk_bf16_f32 v108, v108, v109
	v_cvt_pk_bf16_f32 v109, v118, v119
	global_store_dwordx4 v[128:129], v[106:109], off
	s_nop 1
	v_add_u32_e32 v207, 0x50000, v206
	global_load_dwordx4 v[168:171], v207, s[20:21]
	global_load_dwordx4 v[172:175], v207, s[2:3]
	v_lshl_add_u64 v[114:115], s[2:3], 0, v[114:115]
	s_waitcnt vmcnt(22)
	v_lshlrev_b32_e32 v110, 16, v176
	v_and_b32_e32 v111, 0xffff0000, v176
	v_lshlrev_b32_e32 v112, 16, v177
	v_and_b32_e32 v113, 0xffff0000, v177
	v_lshlrev_b32_e32 v116, 16, v178
	v_and_b32_e32 v117, 0xffff0000, v178
	v_lshlrev_b32_e32 v118, 16, v179
	v_and_b32_e32 v119, 0xffff0000, v179
	s_waitcnt vmcnt(21)
	v_lshlrev_b32_e32 v120, 16, v180
	v_and_b32_e32 v121, 0xffff0000, v180
	v_lshlrev_b32_e32 v106, 16, v181
	v_and_b32_e32 v107, 0xffff0000, v181
	v_pk_fma_f32 v[104:105], v[104:105], v[112:113], v[106:107]
	v_lshlrev_b32_e32 v106, 16, v182
	v_and_b32_e32 v107, 0xffff0000, v182
	v_lshlrev_b32_e32 v108, 16, v183
	v_and_b32_e32 v109, 0xffff0000, v183
	v_pk_fma_f32 v[102:103], v[102:103], v[110:111], v[120:121]
	v_pk_fma_f32 v[108:109], v[100:101], v[118:119], v[108:109]
	v_pk_fma_f32 v[100:101], v[98:99], v[116:117], v[106:107]
	v_cvt_pk_bf16_f32 v98, v102, v103
	v_cvt_pk_bf16_f32 v99, v104, v105
	s_nop 0
	v_cvt_pk_bf16_f32 v100, v100, v101
	v_cvt_pk_bf16_f32 v101, v108, v109
	global_store_dwordx4 v[114:115], v[98:101], off
	s_nop 1
	global_load_dwordx4 v[176:179], v207, s[20:21] offset:256
	global_load_dwordx4 v[180:183], v207, s[2:3] offset:256
	v_or_b32_e32 v98, 32, v132
	v_ashrrev_i32_e32 v99, 31, v98
	v_lshlrev_b64 v[98:99], 10, v[98:99]
	v_lshl_add_u64 v[98:99], v[98:99], 0, v[130:131]
	v_lshlrev_b64 v[98:99], 1, v[98:99]
	v_lshl_add_u64 v[112:113], s[2:3], 0, v[98:99]
	v_or_b32_e32 v98, 0x100, v98
	s_waitcnt vmcnt(23)
	v_lshlrev_b32_e32 v104, 16, v186
	v_and_b32_e32 v105, 0xffff0000, v186
	v_lshlrev_b32_e32 v106, 16, v187
	v_and_b32_e32 v107, 0xffff0000, v187
	v_lshlrev_b32_e32 v108, 16, v188
	v_and_b32_e32 v109, 0xffff0000, v188
	v_lshlrev_b32_e32 v110, 16, v189
	v_and_b32_e32 v111, 0xffff0000, v189
	s_waitcnt vmcnt(22)
	v_lshlrev_b32_e32 v114, 16, v190
	v_and_b32_e32 v115, 0xffff0000, v190
	v_lshlrev_b32_e32 v100, 16, v191
	v_and_b32_e32 v101, 0xffff0000, v191
	v_pk_fma_f32 v[96:97], v[96:97], v[106:107], v[100:101]
	v_lshlrev_b32_e32 v100, 16, v192
	v_and_b32_e32 v101, 0xffff0000, v192
	v_lshlrev_b32_e32 v102, 16, v193
	v_and_b32_e32 v103, 0xffff0000, v193
	v_pk_fma_f32 v[94:95], v[94:95], v[104:105], v[114:115]
	v_pk_fma_f32 v[102:103], v[92:93], v[110:111], v[102:103]
	v_pk_fma_f32 v[92:93], v[90:91], v[108:109], v[100:101]
	v_cvt_pk_bf16_f32 v90, v94, v95
	v_cvt_pk_bf16_f32 v91, v96, v97
	s_nop 0
	v_cvt_pk_bf16_f32 v92, v92, v93
	v_cvt_pk_bf16_f32 v93, v102, v103
	global_store_dwordx4 v[112:113], v[90:93], off
	s_nop 1
	v_add_u32_e32 v207, 0x58000, v206
	global_load_dwordx4 v[186:189], v207, s[20:21]
	global_load_dwordx4 v[190:193], v207, s[2:3]
	v_lshl_add_u64 v[98:99], s[2:3], 0, v[98:99]
	s_waitcnt vmcnt(24)
	v_lshlrev_b32_e32 v94, 16, v194
	v_and_b32_e32 v95, 0xffff0000, v194
	v_lshlrev_b32_e32 v96, 16, v195
	v_and_b32_e32 v97, 0xffff0000, v195
	v_lshlrev_b32_e32 v100, 16, v196
	v_and_b32_e32 v101, 0xffff0000, v196
	v_lshlrev_b32_e32 v102, 16, v197
	v_and_b32_e32 v103, 0xffff0000, v197
	s_waitcnt vmcnt(23)
	v_lshlrev_b32_e32 v104, 16, v198
	v_and_b32_e32 v105, 0xffff0000, v198
	v_lshlrev_b32_e32 v90, 16, v199
	v_and_b32_e32 v91, 0xffff0000, v199
	v_pk_fma_f32 v[88:89], v[88:89], v[96:97], v[90:91]
	v_lshlrev_b32_e32 v90, 16, v200
	v_and_b32_e32 v91, 0xffff0000, v200
	v_lshlrev_b32_e32 v92, 16, v201
	v_and_b32_e32 v93, 0xffff0000, v201
	v_pk_fma_f32 v[86:87], v[86:87], v[94:95], v[104:105]
	v_pk_fma_f32 v[92:93], v[84:85], v[102:103], v[92:93]
	v_pk_fma_f32 v[84:85], v[82:83], v[100:101], v[90:91]
	v_cvt_pk_bf16_f32 v82, v86, v87
	v_cvt_pk_bf16_f32 v83, v88, v89
	s_nop 0
	v_cvt_pk_bf16_f32 v84, v84, v85
	v_cvt_pk_bf16_f32 v85, v92, v93
	global_store_dwordx4 v[98:99], v[82:85], off
	s_nop 1
	global_load_dwordx4 v[194:197], v207, s[20:21] offset:256
	global_load_dwordx4 v[198:201], v207, s[2:3] offset:256
	v_or_b32_e32 v82, 48, v132
	v_ashrrev_i32_e32 v83, 31, v82
	v_lshlrev_b64 v[82:83], 10, v[82:83]
	v_lshl_add_u64 v[82:83], v[82:83], 0, v[130:131]
	v_lshlrev_b64 v[82:83], 1, v[82:83]
	v_lshl_add_u64 v[96:97], s[2:3], 0, v[82:83]
	v_or_b32_e32 v82, 0x100, v82
	s_waitcnt vmcnt(25)
	v_lshlrev_b32_e32 v88, 16, v202
	v_and_b32_e32 v89, 0xffff0000, v202
	v_lshlrev_b32_e32 v90, 16, v203
	v_and_b32_e32 v91, 0xffff0000, v203
	v_lshlrev_b32_e32 v92, 16, v204
	v_and_b32_e32 v93, 0xffff0000, v204
	v_lshlrev_b32_e32 v94, 16, v205
	v_and_b32_e32 v95, 0xffff0000, v205
	s_waitcnt vmcnt(24)
	v_lshlrev_b32_e32 v98, 16, v218
	v_and_b32_e32 v99, 0xffff0000, v218
	v_lshlrev_b32_e32 v84, 16, v219
	v_and_b32_e32 v85, 0xffff0000, v219
	v_pk_fma_f32 v[80:81], v[80:81], v[90:91], v[84:85]
	v_lshlrev_b32_e32 v84, 16, v220
	v_and_b32_e32 v85, 0xffff0000, v220
	v_lshlrev_b32_e32 v86, 16, v221
	v_and_b32_e32 v87, 0xffff0000, v221
	v_pk_fma_f32 v[78:79], v[78:79], v[88:89], v[98:99]
	v_pk_fma_f32 v[86:87], v[76:77], v[94:95], v[86:87]
	v_pk_fma_f32 v[76:77], v[74:75], v[92:93], v[84:85]
	v_cvt_pk_bf16_f32 v74, v78, v79
	v_cvt_pk_bf16_f32 v75, v80, v81
	s_nop 0
	v_cvt_pk_bf16_f32 v76, v76, v77
	v_cvt_pk_bf16_f32 v77, v86, v87
	global_store_dwordx4 v[96:97], v[74:77], off
	s_nop 1
	v_lshl_add_u64 v[82:83], s[2:3], 0, v[82:83]
	s_waitcnt vmcnt(24)
	v_lshlrev_b32_e32 v78, 16, v222
	v_and_b32_e32 v79, 0xffff0000, v222
	v_lshlrev_b32_e32 v80, 16, v223
	v_and_b32_e32 v81, 0xffff0000, v223
	v_lshlrev_b32_e32 v84, 16, v224
	v_and_b32_e32 v85, 0xffff0000, v224
	v_lshlrev_b32_e32 v86, 16, v225
	v_and_b32_e32 v87, 0xffff0000, v225
	s_waitcnt vmcnt(23)
	v_lshlrev_b32_e32 v88, 16, v226
	v_and_b32_e32 v89, 0xffff0000, v226
	v_lshlrev_b32_e32 v74, 16, v227
	v_and_b32_e32 v75, 0xffff0000, v227
	v_pk_fma_f32 v[72:73], v[72:73], v[80:81], v[74:75]
	v_lshlrev_b32_e32 v74, 16, v228
	v_and_b32_e32 v75, 0xffff0000, v228
	v_lshlrev_b32_e32 v76, 16, v229
	v_and_b32_e32 v77, 0xffff0000, v229
	v_pk_fma_f32 v[70:71], v[70:71], v[78:79], v[88:89]
	v_pk_fma_f32 v[76:77], v[68:69], v[86:87], v[76:77]
	v_pk_fma_f32 v[68:69], v[66:67], v[84:85], v[74:75]
	v_cvt_pk_bf16_f32 v66, v70, v71
	v_cvt_pk_bf16_f32 v67, v72, v73
	s_nop 0
	v_cvt_pk_bf16_f32 v68, v68, v69
	v_cvt_pk_bf16_f32 v69, v76, v77
	global_store_dwordx4 v[82:83], v[66:69], off
	s_nop 1
	v_add_u32_e32 v66, 0x80, v132
	v_ashrrev_i32_e32 v67, 31, v66
	v_lshlrev_b64 v[66:67], 10, v[66:67]
	v_lshl_add_u64 v[66:67], v[66:67], 0, v[130:131]
	v_lshlrev_b64 v[66:67], 1, v[66:67]
	v_lshl_add_u64 v[80:81], s[2:3], 0, v[66:67]
	v_or_b32_e32 v66, 0x100, v66
	s_waitcnt vmcnt(23)
	v_lshlrev_b32_e32 v72, 16, v230
	v_and_b32_e32 v73, 0xffff0000, v230
	v_lshlrev_b32_e32 v74, 16, v231
	v_and_b32_e32 v75, 0xffff0000, v231
	v_lshlrev_b32_e32 v76, 16, v232
	v_and_b32_e32 v77, 0xffff0000, v232
	v_lshlrev_b32_e32 v78, 16, v233
	v_and_b32_e32 v79, 0xffff0000, v233
	s_waitcnt vmcnt(22)
	v_lshlrev_b32_e32 v82, 16, v234
	v_and_b32_e32 v83, 0xffff0000, v234
	v_lshlrev_b32_e32 v68, 16, v235
	v_and_b32_e32 v69, 0xffff0000, v235
	v_pk_fma_f32 v[64:65], v[64:65], v[74:75], v[68:69]
	v_lshlrev_b32_e32 v68, 16, v236
	v_and_b32_e32 v69, 0xffff0000, v236
	v_lshlrev_b32_e32 v70, 16, v237
	v_and_b32_e32 v71, 0xffff0000, v237
	v_pk_fma_f32 v[62:63], v[62:63], v[72:73], v[82:83]
	v_pk_fma_f32 v[70:71], v[60:61], v[78:79], v[70:71]
	v_pk_fma_f32 v[60:61], v[58:59], v[76:77], v[68:69]
	v_cvt_pk_bf16_f32 v58, v62, v63
	v_cvt_pk_bf16_f32 v59, v64, v65
	s_nop 0
	v_cvt_pk_bf16_f32 v60, v60, v61
	v_cvt_pk_bf16_f32 v61, v70, v71
	global_store_dwordx4 v[80:81], v[58:61], off
	s_nop 1
	v_lshl_add_u64 v[66:67], s[2:3], 0, v[66:67]
	s_waitcnt vmcnt(22)
	v_lshlrev_b32_e32 v62, 16, v238
	v_and_b32_e32 v63, 0xffff0000, v238
	v_lshlrev_b32_e32 v64, 16, v239
	v_and_b32_e32 v65, 0xffff0000, v239
	v_lshlrev_b32_e32 v68, 16, v240
	v_and_b32_e32 v69, 0xffff0000, v240
	v_lshlrev_b32_e32 v70, 16, v241
	v_and_b32_e32 v71, 0xffff0000, v241
	s_waitcnt vmcnt(21)
	v_lshlrev_b32_e32 v72, 16, v242
	v_and_b32_e32 v73, 0xffff0000, v242
	v_lshlrev_b32_e32 v58, 16, v243
	v_and_b32_e32 v59, 0xffff0000, v243
	v_pk_fma_f32 v[56:57], v[56:57], v[64:65], v[58:59]
	v_lshlrev_b32_e32 v58, 16, v244
	v_and_b32_e32 v59, 0xffff0000, v244
	v_lshlrev_b32_e32 v60, 16, v245
	v_and_b32_e32 v61, 0xffff0000, v245
	v_pk_fma_f32 v[54:55], v[54:55], v[62:63], v[72:73]
	v_pk_fma_f32 v[60:61], v[52:53], v[70:71], v[60:61]
	v_pk_fma_f32 v[52:53], v[50:51], v[68:69], v[58:59]
	v_cvt_pk_bf16_f32 v50, v54, v55
	v_cvt_pk_bf16_f32 v51, v56, v57
	s_nop 0
	v_cvt_pk_bf16_f32 v52, v52, v53
	v_cvt_pk_bf16_f32 v53, v60, v61
	global_store_dwordx4 v[66:67], v[50:53], off
	s_nop 1
	v_add_u32_e32 v50, 0x90, v132
	v_ashrrev_i32_e32 v51, 31, v50
	v_lshlrev_b64 v[50:51], 10, v[50:51]
	v_lshl_add_u64 v[50:51], v[50:51], 0, v[130:131]
	v_lshlrev_b64 v[50:51], 1, v[50:51]
	v_lshl_add_u64 v[64:65], s[2:3], 0, v[50:51]
	v_or_b32_e32 v50, 0x100, v50
	s_waitcnt vmcnt(20)
	v_lshlrev_b32_e32 v56, 16, v152
	v_and_b32_e32 v57, 0xffff0000, v152
	v_lshlrev_b32_e32 v58, 16, v153
	v_and_b32_e32 v59, 0xffff0000, v153
	v_lshlrev_b32_e32 v60, 16, v154
	v_and_b32_e32 v61, 0xffff0000, v154
	v_lshlrev_b32_e32 v62, 16, v155
	v_and_b32_e32 v63, 0xffff0000, v155
	s_waitcnt vmcnt(19)
	v_lshlrev_b32_e32 v66, 16, v156
	v_and_b32_e32 v67, 0xffff0000, v156
	v_lshlrev_b32_e32 v52, 16, v157
	v_and_b32_e32 v53, 0xffff0000, v157
	v_pk_fma_f32 v[48:49], v[48:49], v[58:59], v[52:53]
	v_lshlrev_b32_e32 v52, 16, v158
	v_and_b32_e32 v53, 0xffff0000, v158
	v_lshlrev_b32_e32 v54, 16, v159
	v_and_b32_e32 v55, 0xffff0000, v159
	v_pk_fma_f32 v[46:47], v[46:47], v[56:57], v[66:67]
	v_pk_fma_f32 v[54:55], v[44:45], v[62:63], v[54:55]
	v_pk_fma_f32 v[44:45], v[42:43], v[60:61], v[52:53]
	v_cvt_pk_bf16_f32 v42, v46, v47
	v_cvt_pk_bf16_f32 v43, v48, v49
	s_nop 0
	v_cvt_pk_bf16_f32 v44, v44, v45
	v_cvt_pk_bf16_f32 v45, v54, v55
	global_store_dwordx4 v[64:65], v[42:45], off
	s_nop 1
	v_lshl_add_u64 v[50:51], s[2:3], 0, v[50:51]
	s_waitcnt vmcnt(18)
	v_lshlrev_b32_e32 v46, 16, v160
	v_and_b32_e32 v47, 0xffff0000, v160
	v_lshlrev_b32_e32 v48, 16, v161
	v_and_b32_e32 v49, 0xffff0000, v161
	v_lshlrev_b32_e32 v52, 16, v162
	v_and_b32_e32 v53, 0xffff0000, v162
	v_lshlrev_b32_e32 v54, 16, v163
	v_and_b32_e32 v55, 0xffff0000, v163
	s_waitcnt vmcnt(17)
	v_lshlrev_b32_e32 v56, 16, v164
	v_and_b32_e32 v57, 0xffff0000, v164
	v_lshlrev_b32_e32 v42, 16, v165
	v_and_b32_e32 v43, 0xffff0000, v165
	v_pk_fma_f32 v[40:41], v[40:41], v[48:49], v[42:43]
	v_lshlrev_b32_e32 v42, 16, v166
	v_and_b32_e32 v43, 0xffff0000, v166
	v_lshlrev_b32_e32 v44, 16, v167
	v_and_b32_e32 v45, 0xffff0000, v167
	v_pk_fma_f32 v[38:39], v[38:39], v[46:47], v[56:57]
	v_pk_fma_f32 v[44:45], v[36:37], v[54:55], v[44:45]
	v_pk_fma_f32 v[36:37], v[34:35], v[52:53], v[42:43]
	v_cvt_pk_bf16_f32 v34, v38, v39
	v_cvt_pk_bf16_f32 v35, v40, v41
	s_nop 0
	v_cvt_pk_bf16_f32 v36, v36, v37
	v_cvt_pk_bf16_f32 v37, v44, v45
	global_store_dwordx4 v[50:51], v[34:37], off
	s_nop 1
	v_add_u32_e32 v34, 0xa0, v132
	v_ashrrev_i32_e32 v35, 31, v34
	v_lshlrev_b64 v[34:35], 10, v[34:35]
	v_lshl_add_u64 v[34:35], v[34:35], 0, v[130:131]
	v_lshlrev_b64 v[34:35], 1, v[34:35]
	v_lshl_add_u64 v[48:49], s[2:3], 0, v[34:35]
	v_or_b32_e32 v34, 0x100, v34
	s_waitcnt vmcnt(16)
	v_lshlrev_b32_e32 v40, 16, v168
	v_and_b32_e32 v41, 0xffff0000, v168
	v_lshlrev_b32_e32 v42, 16, v169
	v_and_b32_e32 v43, 0xffff0000, v169
	v_lshlrev_b32_e32 v44, 16, v170
	v_and_b32_e32 v45, 0xffff0000, v170
	v_lshlrev_b32_e32 v46, 16, v171
	v_and_b32_e32 v47, 0xffff0000, v171
	s_waitcnt vmcnt(15)
	v_lshlrev_b32_e32 v50, 16, v172
	v_and_b32_e32 v51, 0xffff0000, v172
	v_lshlrev_b32_e32 v36, 16, v173
	v_and_b32_e32 v37, 0xffff0000, v173
	v_pk_fma_f32 v[32:33], v[32:33], v[42:43], v[36:37]
	v_lshlrev_b32_e32 v36, 16, v174
	v_and_b32_e32 v37, 0xffff0000, v174
	v_lshlrev_b32_e32 v38, 16, v175
	v_and_b32_e32 v39, 0xffff0000, v175
	v_pk_fma_f32 v[30:31], v[30:31], v[40:41], v[50:51]
	v_pk_fma_f32 v[38:39], v[28:29], v[46:47], v[38:39]
	v_pk_fma_f32 v[28:29], v[26:27], v[44:45], v[36:37]
	v_cvt_pk_bf16_f32 v26, v30, v31
	v_cvt_pk_bf16_f32 v27, v32, v33
	s_nop 0
	v_cvt_pk_bf16_f32 v28, v28, v29
	v_cvt_pk_bf16_f32 v29, v38, v39
	global_store_dwordx4 v[48:49], v[26:29], off
	s_nop 1
	v_lshl_add_u64 v[34:35], s[2:3], 0, v[34:35]
	s_waitcnt vmcnt(14)
	v_lshlrev_b32_e32 v30, 16, v176
	v_and_b32_e32 v31, 0xffff0000, v176
	v_lshlrev_b32_e32 v32, 16, v177
	v_and_b32_e32 v33, 0xffff0000, v177
	v_lshlrev_b32_e32 v36, 16, v178
	v_and_b32_e32 v37, 0xffff0000, v178
	v_lshlrev_b32_e32 v38, 16, v179
	v_and_b32_e32 v39, 0xffff0000, v179
	s_waitcnt vmcnt(13)
	v_lshlrev_b32_e32 v40, 16, v180
	v_and_b32_e32 v41, 0xffff0000, v180
	v_lshlrev_b32_e32 v26, 16, v181
	v_and_b32_e32 v27, 0xffff0000, v181
	v_pk_fma_f32 v[24:25], v[24:25], v[32:33], v[26:27]
	v_lshlrev_b32_e32 v26, 16, v182
	v_and_b32_e32 v27, 0xffff0000, v182
	v_lshlrev_b32_e32 v28, 16, v183
	v_and_b32_e32 v29, 0xffff0000, v183
	v_pk_fma_f32 v[22:23], v[22:23], v[30:31], v[40:41]
	v_pk_fma_f32 v[28:29], v[20:21], v[38:39], v[28:29]
	v_pk_fma_f32 v[20:21], v[18:19], v[36:37], v[26:27]
	v_cvt_pk_bf16_f32 v18, v22, v23
	v_cvt_pk_bf16_f32 v19, v24, v25
	s_nop 0
	v_cvt_pk_bf16_f32 v20, v20, v21
	v_cvt_pk_bf16_f32 v21, v28, v29
	global_store_dwordx4 v[34:35], v[18:21], off
	s_nop 1
	v_add_u32_e32 v18, 0xb0, v132
	v_ashrrev_i32_e32 v19, 31, v18
	v_lshlrev_b64 v[18:19], 10, v[18:19]
	v_lshl_add_u64 v[18:19], v[18:19], 0, v[130:131]
	v_lshlrev_b64 v[18:19], 1, v[18:19]
	v_lshl_add_u64 v[32:33], s[2:3], 0, v[18:19]
	v_or_b32_e32 v18, 0x100, v18
	s_waitcnt vmcnt(12)
	v_lshlrev_b32_e32 v24, 16, v186
	v_and_b32_e32 v25, 0xffff0000, v186
	v_lshlrev_b32_e32 v26, 16, v187
	v_and_b32_e32 v27, 0xffff0000, v187
	v_lshlrev_b32_e32 v28, 16, v188
	v_and_b32_e32 v29, 0xffff0000, v188
	v_lshlrev_b32_e32 v30, 16, v189
	v_and_b32_e32 v31, 0xffff0000, v189
	s_waitcnt vmcnt(11)
	v_lshlrev_b32_e32 v34, 16, v190
	v_and_b32_e32 v35, 0xffff0000, v190
	v_lshlrev_b32_e32 v20, 16, v191
	v_and_b32_e32 v21, 0xffff0000, v191
	v_pk_fma_f32 v[16:17], v[16:17], v[26:27], v[20:21]
	v_lshlrev_b32_e32 v20, 16, v192
	v_and_b32_e32 v21, 0xffff0000, v192
	v_lshlrev_b32_e32 v22, 16, v193
	v_and_b32_e32 v23, 0xffff0000, v193
	v_pk_fma_f32 v[14:15], v[14:15], v[24:25], v[34:35]
	v_pk_fma_f32 v[22:23], v[12:13], v[30:31], v[22:23]
	v_pk_fma_f32 v[12:13], v[10:11], v[28:29], v[20:21]
	v_cvt_pk_bf16_f32 v10, v14, v15
	v_cvt_pk_bf16_f32 v11, v16, v17
	s_nop 0
	v_cvt_pk_bf16_f32 v12, v12, v13
	v_cvt_pk_bf16_f32 v13, v22, v23
	global_store_dwordx4 v[32:33], v[10:13], off
	s_nop 1
	v_lshl_add_u64 v[18:19], s[2:3], 0, v[18:19]
	s_mov_b32 s2, s38
	s_waitcnt vmcnt(10)
	v_lshlrev_b32_e32 v14, 16, v194
	v_and_b32_e32 v15, 0xffff0000, v194
	v_lshlrev_b32_e32 v16, 16, v195
	v_and_b32_e32 v17, 0xffff0000, v195
	v_lshlrev_b32_e32 v20, 16, v196
	v_and_b32_e32 v21, 0xffff0000, v196
	v_lshlrev_b32_e32 v22, 16, v197
	v_and_b32_e32 v23, 0xffff0000, v197
	s_waitcnt vmcnt(9)
	v_lshlrev_b32_e32 v24, 16, v198
	v_and_b32_e32 v25, 0xffff0000, v198
	v_lshlrev_b32_e32 v10, 16, v199
	v_and_b32_e32 v11, 0xffff0000, v199
	v_pk_fma_f32 v[8:9], v[8:9], v[16:17], v[10:11]
	v_lshlrev_b32_e32 v10, 16, v200
	v_and_b32_e32 v11, 0xffff0000, v200
	v_lshlrev_b32_e32 v12, 16, v201
	v_and_b32_e32 v13, 0xffff0000, v201
	v_pk_fma_f32 v[6:7], v[6:7], v[14:15], v[24:25]
	v_pk_fma_f32 v[12:13], v[4:5], v[22:23], v[12:13]
	v_pk_fma_f32 v[4:5], v[2:3], v[20:21], v[10:11]
	v_cvt_pk_bf16_f32 v2, v6, v7
	v_cvt_pk_bf16_f32 v3, v8, v9
	s_nop 0
	v_cvt_pk_bf16_f32 v4, v4, v5
	v_cvt_pk_bf16_f32 v5, v12, v13
	global_store_dwordx4 v[18:19], v[2:5], off
	v_mbcnt_lo_u32_b32 v130, -1, 0
	v_mbcnt_hi_u32_b32 v130, -1, v130
	v_lshl_add_u32 v130, s69, 6, v130
	s_nop 0
	v_lshlrev_b32_e32 v12, 4, v130
	v_bfe_i32 v2, v130, 27, 1
	v_lshrrev_b32_e32 v2, 22, v2
	v_add_u32_e32 v2, v12, v2
	v_and_b32_e32 v2, 0xfffffc00, v2
	v_ashrrev_i32_e32 v0, 31, v130
	v_sub_u32_e32 v2, v12, v2
	v_lshrrev_b32_e32 v0, 26, v0
	v_lshrrev_b32_e32 v3, 4, v2
	v_add_u32_e32 v0, v130, v0
	v_bitop3_b32 v3, v3, v2, 32 bitop3:0x6c
	v_ashrrev_i32_e32 v2, 31, v2
	v_ashrrev_i32_e32 v0, 6, v0
	v_lshrrev_b32_e32 v2, 26, v2
	v_lshlrev_b32_e32 v4, 3, v0
	v_add_u32_e32 v2, v3, v2
	v_and_b32_e32 v4, -16, v4
	v_ashrrev_i32_e32 v2, 6, v2
	v_add_u32_e32 v4, v2, v4
	v_mul_i32_i24_e32 v2, 64, v2
	v_lshlrev_b32_e32 v0, 5, v0
	v_sub_u32_e32 v2, v3, v2
	v_add_u32_e32 v13, 0x2000, v12
	v_and_b32_e32 v0, 32, v0
	v_ashrrev_i16_sdwa v2, v217, sext(v2) dst_sel:DWORD dst_unused:UNUSED_PAD src0_sel:DWORD src1_sel:BYTE_0
	v_add_u32_sdwa v0, v0, sext(v2) dst_sel:DWORD dst_unused:UNUSED_PAD src0_sel:DWORD src1_sel:WORD_0
	v_ashrrev_i32_e32 v2, 31, v13
	v_lshrrev_b32_e32 v2, 22, v2
	v_add_u32_e32 v2, v13, v2
	v_ashrrev_i32_e32 v2, 10, v2
	v_mul_i32_i24_e32 v3, 0x400, v2
	v_sub_u32_e32 v3, v13, v3
	v_lshrrev_b32_e32 v5, 4, v3
	v_bitop3_b32 v3, v5, v3, 32 bitop3:0x6c
	v_ashrrev_i32_e32 v6, 31, v3
	v_lshrrev_b32_e32 v6, 26, v6
	v_add_u32_e32 v6, v3, v6
	v_ashrrev_i32_e32 v7, 6, v6
	v_and_b32_e32 v6, 0xc0, v6
	v_lshlrev_b32_e32 v5, 3, v2
	v_lshlrev_b32_e32 v2, 5, v2
	v_sub_u32_e32 v3, v3, v6
	v_and_b32_e32 v5, -16, v5
	v_and_b32_e32 v2, 32, v2
	v_ashrrev_i16_sdwa v3, v217, sext(v3) dst_sel:DWORD dst_unused:UNUSED_PAD src0_sel:DWORD src1_sel:BYTE_0
	v_add_u32_e32 v5, v7, v5
	v_add_u32_sdwa v2, v2, sext(v3) dst_sel:DWORD dst_unused:UNUSED_PAD src0_sel:DWORD src1_sel:WORD_0
	v_mul_lo_u32 v3, v4, s59
	v_add_lshl_u32 v11, v0, v3, 1
	v_mul_lo_u32 v3, v5, s59
	v_add_lshl_u32 v10, v2, v3, 1
	v_lshlrev_b32_e32 v3, 9, v4
	v_lshl_add_u32 v0, v0, 1, v3
	v_lshlrev_b32_e32 v3, 9, v5
	v_ashrrev_i32_e32 v14, 6, v130
	v_lshl_add_u32 v2, v2, 1, v3
	s_cbranch_vccnz .LBB0_80
